# v52 + layer-0 ffn gate/up weight conversion moved out of phase 0 into phase 1, staggered around the GEMM tiles (WGs 0-127 before, 128-255 after)
# speedup vs baseline: 1.0313x; 1.0026x over previous
; #define LAS __attribute__((address_space(3)))
; __device__ __forceinline__ void xpose_item(const float* src, int ld, bf16_t* dst, int K, int k0, LAS float* scr, int lane, const float* gk) {
;     if (src) {
; #pragma unroll 8
;         for (int i = 0; i < 32; ++i) { const int kk = 2 * i + (lane >> 5); scr[kk * 33 + (lane & 31)] = __builtin_nontemporal_load(src + (size_t)(k0 + kk) * ld + (lane & 31)); }
;     } else {
; #pragma unroll 8
;         for (int i = 0; i < 32; ++i) { const int kk = 2 * i + (lane >> 5); scr[kk * 33 + (lane & 31)] = 0.f; }
;     }
;     const int c = lane & 7;
;     f32x4 g0 = (f32x4){1.f, 1.f, 1.f, 1.f}, g1 = g0;
;     if (gk) { g0 = *(const f32x4*)(gk + k0 + 8 * c); g1 = *(const f32x4*)(gk + k0 + 8 * c + 4); }
; __global__ void __launch_bounds__(512) mega(Args a_byval) {
;     ...
;         case 1: if (!PH_ON(1)) break; {
;             pg8::Gemm g{U, (const bf16_t*)(ws + WS_W_IN), T, 4096, 2048, 2048, 2048, 0}; pg8::StaticOrder S; S.init(T, 4096, G, bid);
;             EpiXY E{(bf16_t*)(ws + WS_XRPRE), (bf16_t*)(ws + WS_YG)}; pg8::gemm_phase(lds, g, S, E, tid);
.LBB0_521:
	s_andn2_b64 vcc, exec, s[0:1]
	s_cbranch_vccnz .LBB0_586
	s_cmp_gt_i32 s76, 0
	s_mov_b64 s[0:1], -1
	s_cbranch_scc0 .LBB0_584
	s_cmp_lg_u32 s76, 1
	s_cbranch_scc1 .Lsgp1e_done
	v_readlane_b32 s59, v255, 5
	s_cmpk_lg_i32 s59, 0x100
	s_cbranch_scc1 .Lsgp1e_done
	s_cmpk_gt_i32 s94, 0x7f
	s_cbranch_scc1 .Lsgp1e_done
	s_lshl_b32 s59, s94, 3
	s_add_i32 s59, s59, s95
	s_mul_i32 s64, s95, 0x2100
	v_and_b32_e32 v2, 31, v200
	v_lshrrev_b32_e32 v3, 5, v200
	v_lshlrev_b32_e32 v4, 2, v2
	v_mul_u32_u24_e32 v6, 0x84, v3
	v_add3_u32 v6, v6, v4, s64
	v_and_b32_e32 v7, 7, v200
	v_lshrrev_b32_e32 v8, 3, v200
	v_mul_u32_u24_e32 v9, 0x420, v7
	v_lshl_add_u32 v9, v8, 2, v9
	v_add_u32_e32 v9, s64, v9
	s_cmpk_ge_i32 s59, 0x2c00
	s_cbranch_scc1 .Lxpg0p1e_end
	s_load_dwordx2 s[60:61], s[92:93], 0xb8
	s_load_dwordx2 s[62:63], s[92:93], 0xe8
	s_load_dwordx2 s[64:65], s[92:93], 0x18
	v_mov_b32_e32 v5, 0x5800
	v_mul_u32_u24_e32 v5, v3, v5
	v_add_u32_e32 v5, v5, v4
	v_mov_b32_e32 v10, 0x1000
	v_mul_u32_u24_e32 v10, v8, v10
	v_lshl_add_u32 v12, v7, 4, v10
	v_add_u32_e32 v13, 0x8000, v12
	v_add_u32_e32 v14, 0x10000, v12
	v_add_u32_e32 v15, 0x18000, v12
	s_waitcnt lgkmcnt(0)
	s_add_u32 s62, s62, 0x1cc00000
	s_addc_u32 s63, s63, 0
	s_add_u32 s64, s64, 0x0
	s_addc_u32 s65, s65, 0
	v_lshlrev_b32_e32 v16, 5, v7
	v_mov_b32_e32 v17, v0
	v_lshl_add_u64 v[16:17], s[64:65], 0, v[16:17]
	s_mul_hi_u32 s64, s59, 0xba2e8c
	s_mul_i32 s65, s64, 0x160
	s_sub_i32 s65, s59, s65
	s_mul_i32 s68, s64, 0x160000
	s_lshr_b32 s66, s65, 3
	s_lshl_b32 s66, s66, 9
	s_add_i32 s68, s68, s66
	s_and_b32 s66, s65, 3
	s_lshl_b32 s66, s66, 7
	s_add_i32 s68, s68, s66
	s_add_i32 s68, s68, 0x0
	s_bitcmp1_b32 s65, 2
	s_movk_i32 s33, 0xb8
	s_cselect_b32 s33, 0xc0, s33
	s_load_dwordx2 s[66:67], s[92:93], s33
	s_waitcnt lgkmcnt(0)
	s_add_u32 s66, s66, s68
	s_addc_u32 s67, s67, 0
	s_lshl_b32 s64, s64, 8
	s_mov_b32 s65, 0
	v_lshl_add_u64 v[18:19], s[64:65], 0, v[16:17]
	global_load_dwordx4 v[52:55], v[18:19], off
	global_load_dwordx4 v[56:59], v[18:19], off offset:16
	v_mov_b32_e32 v11, v5
	global_load_dword v20, v11, s[66:67] nt
	v_add_u32_e32 v11, 0xb000, v11
	global_load_dword v21, v11, s[66:67] nt
	v_add_u32_e32 v11, 0xb000, v11
	global_load_dword v22, v11, s[66:67] nt
	v_add_u32_e32 v11, 0xb000, v11
	global_load_dword v23, v11, s[66:67] nt
	v_add_u32_e32 v11, 0xb000, v11
	global_load_dword v24, v11, s[66:67] nt
	v_add_u32_e32 v11, 0xb000, v11
	global_load_dword v25, v11, s[66:67] nt
	v_add_u32_e32 v11, 0xb000, v11
	global_load_dword v26, v11, s[66:67] nt
	v_add_u32_e32 v11, 0xb000, v11
	global_load_dword v27, v11, s[66:67] nt
	v_add_u32_e32 v11, 0xb000, v11
	global_load_dword v28, v11, s[66:67] nt
	v_add_u32_e32 v11, 0xb000, v11
	global_load_dword v29, v11, s[66:67] nt
	v_add_u32_e32 v11, 0xb000, v11
	global_load_dword v30, v11, s[66:67] nt
	v_add_u32_e32 v11, 0xb000, v11
	global_load_dword v31, v11, s[66:67] nt
	v_add_u32_e32 v11, 0xb000, v11
	global_load_dword v32, v11, s[66:67] nt
	v_add_u32_e32 v11, 0xb000, v11
	global_load_dword v33, v11, s[66:67] nt
	v_add_u32_e32 v11, 0xb000, v11
	global_load_dword v34, v11, s[66:67] nt
	v_add_u32_e32 v11, 0xb000, v11
	global_load_dword v35, v11, s[66:67] nt
	v_add_u32_e32 v11, 0xb000, v11
	global_load_dword v36, v11, s[66:67] nt
	v_add_u32_e32 v11, 0xb000, v11
	global_load_dword v37, v11, s[66:67] nt
	v_add_u32_e32 v11, 0xb000, v11
	global_load_dword v38, v11, s[66:67] nt
	v_add_u32_e32 v11, 0xb000, v11
	global_load_dword v39, v11, s[66:67] nt
	v_add_u32_e32 v11, 0xb000, v11
	global_load_dword v40, v11, s[66:67] nt
	v_add_u32_e32 v11, 0xb000, v11
	global_load_dword v41, v11, s[66:67] nt
	v_add_u32_e32 v11, 0xb000, v11
	global_load_dword v42, v11, s[66:67] nt
	v_add_u32_e32 v11, 0xb000, v11
	global_load_dword v43, v11, s[66:67] nt
	v_add_u32_e32 v11, 0xb000, v11
	global_load_dword v44, v11, s[66:67] nt
	v_add_u32_e32 v11, 0xb000, v11
	global_load_dword v45, v11, s[66:67] nt
	v_add_u32_e32 v11, 0xb000, v11
	global_load_dword v46, v11, s[66:67] nt
	v_add_u32_e32 v11, 0xb000, v11
	global_load_dword v47, v11, s[66:67] nt
	v_add_u32_e32 v11, 0xb000, v11
	global_load_dword v48, v11, s[66:67] nt
	v_add_u32_e32 v11, 0xb000, v11
	global_load_dword v49, v11, s[66:67] nt
	v_add_u32_e32 v11, 0xb000, v11
	global_load_dword v50, v11, s[66:67] nt
	v_add_u32_e32 v11, 0xb000, v11
	global_load_dword v51, v11, s[66:67] nt
; #define LAS __attribute__((address_space(3)))
; __device__ __forceinline__ void xpose_item(const float* src, int ld, bf16_t* dst, int K, int k0, LAS float* scr, int lane, const float* gk) {
;     if (src) {
; #pragma unroll 8
;         for (int i = 0; i < 32; ++i) { const int kk = 2 * i + (lane >> 5); scr[kk * 33 + (lane & 31)] = __builtin_nontemporal_load(src + (size_t)(k0 + kk) * ld + (lane & 31)); }
;     } else {
; #pragma unroll 8
;         for (int i = 0; i < 32; ++i) { const int kk = 2 * i + (lane >> 5); scr[kk * 33 + (lane & 31)] = 0.f; }
;     }
;     const int c = lane & 7;
;     f32x4 g0 = (f32x4){1.f, 1.f, 1.f, 1.f}, g1 = g0;
;     if (gk) { g0 = *(const f32x4*)(gk + k0 + 8 * c); g1 = *(const f32x4*)(gk + k0 + 8 * c + 4); }
.Lxpg0p1e_loop:
	s_add_i32 s32, s59, 0x800
	s_cmpk_lt_i32 s32, 0x2c00
	s_cbranch_scc0 .Lxpg0p1e_dumB
	s_mul_hi_u32 s64, s32, 0xba2e8c
	s_mul_i32 s65, s64, 0x160
	s_sub_i32 s65, s32, s65
	s_mul_i32 s68, s64, 0x160000
	s_lshr_b32 s66, s65, 3
	s_lshl_b32 s66, s66, 9
	s_add_i32 s68, s68, s66
	s_and_b32 s66, s65, 3
	s_lshl_b32 s66, s66, 7
	s_add_i32 s68, s68, s66
	s_add_i32 s68, s68, 0x0
	s_bitcmp1_b32 s65, 2
	s_movk_i32 s33, 0xb8
	s_cselect_b32 s33, 0xc0, s33
	s_load_dwordx2 s[66:67], s[92:93], s33
	s_waitcnt lgkmcnt(0)
	s_add_u32 s66, s66, s68
	s_addc_u32 s67, s67, 0
	s_lshl_b32 s64, s64, 8
	s_mov_b32 s65, 0
	v_lshl_add_u64 v[18:19], s[64:65], 0, v[16:17]
	global_load_dwordx4 v[160:163], v[18:19], off
	global_load_dwordx4 v[164:167], v[18:19], off offset:16
	v_mov_b32_e32 v11, v5
	global_load_dword v108, v11, s[66:67] nt
	v_add_u32_e32 v11, 0xb000, v11
	global_load_dword v109, v11, s[66:67] nt
	v_add_u32_e32 v11, 0xb000, v11
	global_load_dword v110, v11, s[66:67] nt
	v_add_u32_e32 v11, 0xb000, v11
	global_load_dword v111, v11, s[66:67] nt
	v_add_u32_e32 v11, 0xb000, v11
	global_load_dword v112, v11, s[66:67] nt
	v_add_u32_e32 v11, 0xb000, v11
	global_load_dword v113, v11, s[66:67] nt
	v_add_u32_e32 v11, 0xb000, v11
	global_load_dword v114, v11, s[66:67] nt
	v_add_u32_e32 v11, 0xb000, v11
	global_load_dword v115, v11, s[66:67] nt
	v_add_u32_e32 v11, 0xb000, v11
	global_load_dword v116, v11, s[66:67] nt
	v_add_u32_e32 v11, 0xb000, v11
	global_load_dword v117, v11, s[66:67] nt
	v_add_u32_e32 v11, 0xb000, v11
	global_load_dword v118, v11, s[66:67] nt
	v_add_u32_e32 v11, 0xb000, v11
	global_load_dword v119, v11, s[66:67] nt
	v_add_u32_e32 v11, 0xb000, v11
	global_load_dword v120, v11, s[66:67] nt
	v_add_u32_e32 v11, 0xb000, v11
	global_load_dword v121, v11, s[66:67] nt
	v_add_u32_e32 v11, 0xb000, v11
	global_load_dword v122, v11, s[66:67] nt
	v_add_u32_e32 v11, 0xb000, v11
	global_load_dword v123, v11, s[66:67] nt
	v_add_u32_e32 v11, 0xb000, v11
	global_load_dword v124, v11, s[66:67] nt
	v_add_u32_e32 v11, 0xb000, v11
	global_load_dword v125, v11, s[66:67] nt
	v_add_u32_e32 v11, 0xb000, v11
	global_load_dword v126, v11, s[66:67] nt
	v_add_u32_e32 v11, 0xb000, v11
	global_load_dword v127, v11, s[66:67] nt
	v_add_u32_e32 v11, 0xb000, v11
	global_load_dword v128, v11, s[66:67] nt
	v_add_u32_e32 v11, 0xb000, v11
	global_load_dword v129, v11, s[66:67] nt
	v_add_u32_e32 v11, 0xb000, v11
	global_load_dword v130, v11, s[66:67] nt
	v_add_u32_e32 v11, 0xb000, v11
	global_load_dword v131, v11, s[66:67] nt
	v_add_u32_e32 v11, 0xb000, v11
	global_load_dword v132, v11, s[66:67] nt
	v_add_u32_e32 v11, 0xb000, v11
	global_load_dword v133, v11, s[66:67] nt
	v_add_u32_e32 v11, 0xb000, v11
	global_load_dword v134, v11, s[66:67] nt
	v_add_u32_e32 v11, 0xb000, v11
	global_load_dword v135, v11, s[66:67] nt
	v_add_u32_e32 v11, 0xb000, v11
	global_load_dword v136, v11, s[66:67] nt
	v_add_u32_e32 v11, 0xb000, v11
	global_load_dword v137, v11, s[66:67] nt
	v_add_u32_e32 v11, 0xb000, v11
	global_load_dword v138, v11, s[66:67] nt
	v_add_u32_e32 v11, 0xb000, v11
	global_load_dword v139, v11, s[66:67] nt
	s_branch .Lxpg0p1e_procA

; #define LAS __attribute__((address_space(3)))
; __device__ __forceinline__ unsigned cvt_pk_bf16(float lo, float hi) { unsigned r; asm volatile("v_cvt_pk_bf16_f32 %0, %1, %2" : "=v"(r) : "v"(lo), "v"(hi)); return r; }
; __device__ __forceinline__ void xpose_item(const float* src, int ld, bf16_t* dst, int K, int k0, LAS float* scr, int lane, const float* gk) {
;     ...
;         for (int i = 0; i < 32; ++i) { const int kk = 2 * i + (lane >> 5); scr[kk * 33 + (lane & 31)] = __builtin_nontemporal_load(src + (size_t)(k0 + kk) * ld + (lane & 31)); }
;     } else {
; #pragma unroll 8
;         for (int i = 0; i < 32; ++i) { const int kk = 2 * i + (lane >> 5); scr[kk * 33 + (lane & 31)] = 0.f; }
;     }
;     const int c = lane & 7;
;     f32x4 g0 = (f32x4){1.f, 1.f, 1.f, 1.f}, g1 = g0;
;     if (gk) { g0 = *(const f32x4*)(gk + k0 + 8 * c); g1 = *(const f32x4*)(gk + k0 + 8 * c + 4); }
;     asm volatile("s_waitcnt lgkmcnt(0)" ::: "memory");
; #pragma unroll
;     for (int j = 0; j < 4; ++j) { const int n = (lane >> 3) + 8 * j; const LAS float* s = scr + (8 * c) * 33 + n;
;         u32x4 o; o.x = cvt_pk_bf16(s[0 * 33] * g0[0], s[1 * 33] * g0[1]); o.y = cvt_pk_bf16(s[2 * 33] * g0[2], s[3 * 33] * g0[3]); o.z = cvt_pk_bf16(s[4 * 33] * g1[0], s[5 * 33] * g1[1]); o.w = cvt_pk_bf16(s[6 * 33] * g1[2], s[7 * 33] * g1[3]);
;         *(u32x4*)(dst + (size_t)n * K + k0 + 8 * c) = o; }
.Lxpg0p1e_procA:
	s_mul_hi_u32 s64, s59, 0xba2e8c
	s_mul_i32 s65, s64, 0x160
	s_sub_i32 s65, s59, s65
	s_mul_i32 s68, s65, 0x20000
	s_lshl_b32 s64, s64, 7
	s_add_i32 s68, s68, s64
	s_add_u32 s64, s62, s68
	s_addc_u32 s65, s63, 0
	s_waitcnt vmcnt(63)
	ds_write_b32 v6, v20 offset:0
	s_waitcnt vmcnt(62)
	ds_write_b32 v6, v21 offset:264
	s_waitcnt vmcnt(61)
	ds_write_b32 v6, v22 offset:528
	s_waitcnt vmcnt(60)
	ds_write_b32 v6, v23 offset:792
	s_waitcnt vmcnt(59)
	ds_write_b32 v6, v24 offset:1056
	s_waitcnt vmcnt(58)
	ds_write_b32 v6, v25 offset:1320
	s_waitcnt vmcnt(57)
	ds_write_b32 v6, v26 offset:1584
	s_waitcnt vmcnt(56)
	ds_write_b32 v6, v27 offset:1848
	s_waitcnt vmcnt(55)
	ds_write_b32 v6, v28 offset:2112
	s_waitcnt vmcnt(54)
	ds_write_b32 v6, v29 offset:2376
	s_waitcnt vmcnt(53)
	ds_write_b32 v6, v30 offset:2640
	s_waitcnt vmcnt(52)
	ds_write_b32 v6, v31 offset:2904
	s_waitcnt vmcnt(51)
	ds_write_b32 v6, v32 offset:3168
	s_waitcnt vmcnt(50)
	ds_write_b32 v6, v33 offset:3432
	s_waitcnt vmcnt(49)
	ds_write_b32 v6, v34 offset:3696
	s_waitcnt vmcnt(48)
	ds_write_b32 v6, v35 offset:3960
	s_waitcnt vmcnt(47)
	ds_write_b32 v6, v36 offset:4224
	s_waitcnt vmcnt(46)
	ds_write_b32 v6, v37 offset:4488
	s_waitcnt vmcnt(45)
	ds_write_b32 v6, v38 offset:4752
	s_waitcnt vmcnt(44)
	ds_write_b32 v6, v39 offset:5016
	s_waitcnt vmcnt(43)
	ds_write_b32 v6, v40 offset:5280
	s_waitcnt vmcnt(42)
	ds_write_b32 v6, v41 offset:5544
	s_waitcnt vmcnt(41)
	ds_write_b32 v6, v42 offset:5808
	s_waitcnt vmcnt(40)
	ds_write_b32 v6, v43 offset:6072
	s_waitcnt vmcnt(39)
	ds_write_b32 v6, v44 offset:6336
	s_waitcnt vmcnt(38)
	ds_write_b32 v6, v45 offset:6600
	s_waitcnt vmcnt(37)
	ds_write_b32 v6, v46 offset:6864
	s_waitcnt vmcnt(36)
	ds_write_b32 v6, v47 offset:7128
	s_waitcnt vmcnt(35)
	ds_write_b32 v6, v48 offset:7392
	s_waitcnt vmcnt(34)
	ds_write_b32 v6, v49 offset:7656
	s_waitcnt vmcnt(33)
	ds_write_b32 v6, v50 offset:7920
	s_waitcnt vmcnt(32)
	ds_write_b32 v6, v51 offset:8184
	s_waitcnt lgkmcnt(0)
	ds_read2_b32 v[60:61], v9 offset0:0 offset1:33
	ds_read2_b32 v[62:63], v9 offset0:66 offset1:99
	ds_read2_b32 v[64:65], v9 offset0:132 offset1:165
	ds_read2_b32 v[66:67], v9 offset0:198 offset1:231
	ds_read2_b32 v[68:69], v9 offset0:8 offset1:41
	ds_read2_b32 v[70:71], v9 offset0:74 offset1:107
	ds_read2_b32 v[72:73], v9 offset0:140 offset1:173
	ds_read2_b32 v[74:75], v9 offset0:206 offset1:239
	ds_read2_b32 v[76:77], v9 offset0:16 offset1:49
	ds_read2_b32 v[78:79], v9 offset0:82 offset1:115
	ds_read2_b32 v[80:81], v9 offset0:148 offset1:181
	ds_read2_b32 v[82:83], v9 offset0:214 offset1:247
	ds_read2_b32 v[84:85], v9 offset0:24 offset1:57
	ds_read2_b32 v[86:87], v9 offset0:90 offset1:123
	ds_read2_b32 v[88:89], v9 offset0:156 offset1:189
	ds_read2_b32 v[90:91], v9 offset0:222 offset1:255
	s_waitcnt lgkmcnt(12)
	v_mul_f32_e32 v60, v60, v52
	v_mul_f32_e32 v61, v61, v53
	v_mul_f32_e32 v62, v62, v54
	v_mul_f32_e32 v63, v63, v55
	v_mul_f32_e32 v64, v64, v56
	v_mul_f32_e32 v65, v65, v57
	v_mul_f32_e32 v66, v66, v58
	v_mul_f32_e32 v67, v67, v59
	v_cvt_pk_bf16_f32 v92, v60, v61
	v_cvt_pk_bf16_f32 v93, v62, v63
	v_cvt_pk_bf16_f32 v94, v64, v65
	v_cvt_pk_bf16_f32 v95, v66, v67
	global_store_dwordx4 v12, v[92:95], s[64:65]
	s_waitcnt lgkmcnt(8)
	v_mul_f32_e32 v68, v68, v52
	v_mul_f32_e32 v69, v69, v53
	v_mul_f32_e32 v70, v70, v54
	v_mul_f32_e32 v71, v71, v55
	v_mul_f32_e32 v72, v72, v56
	v_mul_f32_e32 v73, v73, v57
	v_mul_f32_e32 v74, v74, v58
	v_mul_f32_e32 v75, v75, v59
	v_cvt_pk_bf16_f32 v96, v68, v69
	v_cvt_pk_bf16_f32 v97, v70, v71
	v_cvt_pk_bf16_f32 v98, v72, v73
	v_cvt_pk_bf16_f32 v99, v74, v75
	global_store_dwordx4 v13, v[96:99], s[64:65]
	s_waitcnt lgkmcnt(4)
	v_mul_f32_e32 v76, v76, v52
	v_mul_f32_e32 v77, v77, v53
	v_mul_f32_e32 v78, v78, v54
	v_mul_f32_e32 v79, v79, v55
	v_mul_f32_e32 v80, v80, v56
	v_mul_f32_e32 v81, v81, v57
	v_mul_f32_e32 v82, v82, v58
	v_mul_f32_e32 v83, v83, v59
	v_cvt_pk_bf16_f32 v100, v76, v77
	v_cvt_pk_bf16_f32 v101, v78, v79
	v_cvt_pk_bf16_f32 v102, v80, v81
	v_cvt_pk_bf16_f32 v103, v82, v83
	global_store_dwordx4 v14, v[100:103], s[64:65]
	s_waitcnt lgkmcnt(0)
	v_mul_f32_e32 v84, v84, v52
	v_mul_f32_e32 v85, v85, v53
	v_mul_f32_e32 v86, v86, v54
	v_mul_f32_e32 v87, v87, v55
	v_mul_f32_e32 v88, v88, v56
	v_mul_f32_e32 v89, v89, v57
	v_mul_f32_e32 v90, v90, v58
	v_mul_f32_e32 v91, v91, v59
	v_cvt_pk_bf16_f32 v104, v84, v85
	v_cvt_pk_bf16_f32 v105, v86, v87
	v_cvt_pk_bf16_f32 v106, v88, v89
	v_cvt_pk_bf16_f32 v107, v90, v91
	global_store_dwordx4 v15, v[104:107], s[64:65]
	s_cmpk_lt_i32 s32, 0x2c00
	s_cbranch_scc0 .Lxpg0p1e_fin
; #define LAS __attribute__((address_space(3)))
; __device__ __forceinline__ void xpose_item(const float* src, int ld, bf16_t* dst, int K, int k0, LAS float* scr, int lane, const float* gk) {
;     if (src) {
; #pragma unroll 8
;         for (int i = 0; i < 32; ++i) { const int kk = 2 * i + (lane >> 5); scr[kk * 33 + (lane & 31)] = __builtin_nontemporal_load(src + (size_t)(k0 + kk) * ld + (lane & 31)); }
;     } else {
; #pragma unroll 8
;         for (int i = 0; i < 32; ++i) { const int kk = 2 * i + (lane >> 5); scr[kk * 33 + (lane & 31)] = 0.f; }
;     }
;     const int c = lane & 7;
;     f32x4 g0 = (f32x4){1.f, 1.f, 1.f, 1.f}, g1 = g0;
;     if (gk) { g0 = *(const f32x4*)(gk + k0 + 8 * c); g1 = *(const f32x4*)(gk + k0 + 8 * c + 4); }
	s_add_i32 s59, s32, 0x800
	s_cmpk_lt_i32 s59, 0x2c00
	s_cbranch_scc0 .Lxpg0p1e_dumA
	s_mul_hi_u32 s64, s59, 0xba2e8c
	s_mul_i32 s65, s64, 0x160
	s_sub_i32 s65, s59, s65
	s_mul_i32 s68, s64, 0x160000
	s_lshr_b32 s66, s65, 3
	s_lshl_b32 s66, s66, 9
	s_add_i32 s68, s68, s66
	s_and_b32 s66, s65, 3
	s_lshl_b32 s66, s66, 7
	s_add_i32 s68, s68, s66
	s_add_i32 s68, s68, 0x0
	s_bitcmp1_b32 s65, 2
	s_movk_i32 s33, 0xb8
	s_cselect_b32 s33, 0xc0, s33
	s_load_dwordx2 s[66:67], s[92:93], s33
	s_waitcnt lgkmcnt(0)
	s_add_u32 s66, s66, s68
	s_addc_u32 s67, s67, 0
	s_lshl_b32 s64, s64, 8
	s_mov_b32 s65, 0
	v_lshl_add_u64 v[18:19], s[64:65], 0, v[16:17]
	global_load_dwordx4 v[52:55], v[18:19], off
	global_load_dwordx4 v[56:59], v[18:19], off offset:16
	v_mov_b32_e32 v11, v5
	global_load_dword v20, v11, s[66:67] nt
	v_add_u32_e32 v11, 0xb000, v11
	global_load_dword v21, v11, s[66:67] nt
	v_add_u32_e32 v11, 0xb000, v11
	global_load_dword v22, v11, s[66:67] nt
	v_add_u32_e32 v11, 0xb000, v11
	global_load_dword v23, v11, s[66:67] nt
	v_add_u32_e32 v11, 0xb000, v11
	global_load_dword v24, v11, s[66:67] nt
	v_add_u32_e32 v11, 0xb000, v11
	global_load_dword v25, v11, s[66:67] nt
	v_add_u32_e32 v11, 0xb000, v11
	global_load_dword v26, v11, s[66:67] nt
	v_add_u32_e32 v11, 0xb000, v11
	global_load_dword v27, v11, s[66:67] nt
	v_add_u32_e32 v11, 0xb000, v11
	global_load_dword v28, v11, s[66:67] nt
	v_add_u32_e32 v11, 0xb000, v11
	global_load_dword v29, v11, s[66:67] nt
	v_add_u32_e32 v11, 0xb000, v11
	global_load_dword v30, v11, s[66:67] nt
	v_add_u32_e32 v11, 0xb000, v11
	global_load_dword v31, v11, s[66:67] nt
	v_add_u32_e32 v11, 0xb000, v11
	global_load_dword v32, v11, s[66:67] nt
	v_add_u32_e32 v11, 0xb000, v11
	global_load_dword v33, v11, s[66:67] nt
	v_add_u32_e32 v11, 0xb000, v11
	global_load_dword v34, v11, s[66:67] nt
	v_add_u32_e32 v11, 0xb000, v11
	global_load_dword v35, v11, s[66:67] nt
	v_add_u32_e32 v11, 0xb000, v11
	global_load_dword v36, v11, s[66:67] nt
	v_add_u32_e32 v11, 0xb000, v11
	global_load_dword v37, v11, s[66:67] nt
	v_add_u32_e32 v11, 0xb000, v11
	global_load_dword v38, v11, s[66:67] nt
	v_add_u32_e32 v11, 0xb000, v11
	global_load_dword v39, v11, s[66:67] nt
	v_add_u32_e32 v11, 0xb000, v11
	global_load_dword v40, v11, s[66:67] nt
	v_add_u32_e32 v11, 0xb000, v11
	global_load_dword v41, v11, s[66:67] nt
	v_add_u32_e32 v11, 0xb000, v11
	global_load_dword v42, v11, s[66:67] nt
	v_add_u32_e32 v11, 0xb000, v11
	global_load_dword v43, v11, s[66:67] nt
	v_add_u32_e32 v11, 0xb000, v11
	global_load_dword v44, v11, s[66:67] nt
	v_add_u32_e32 v11, 0xb000, v11
	global_load_dword v45, v11, s[66:67] nt
	v_add_u32_e32 v11, 0xb000, v11
	global_load_dword v46, v11, s[66:67] nt
	v_add_u32_e32 v11, 0xb000, v11
	global_load_dword v47, v11, s[66:67] nt
	v_add_u32_e32 v11, 0xb000, v11
	global_load_dword v48, v11, s[66:67] nt
	v_add_u32_e32 v11, 0xb000, v11
	global_load_dword v49, v11, s[66:67] nt
	v_add_u32_e32 v11, 0xb000, v11
	global_load_dword v50, v11, s[66:67] nt
	v_add_u32_e32 v11, 0xb000, v11
	global_load_dword v51, v11, s[66:67] nt
	s_branch .Lxpg0p1e_procB

;     __device__ bool next(int i, Unit& u) const {
;         const long L = (long)i * G + c; if (L >= nwg) return false;
;         int wgid = (int)L; { const int q = nwg / NXCD, r = nwg % NXCD, xcd = wgid % NXCD, off = wgid / NXCD; wgid = (xcd < r ? xcd * (q + 1) : r * (q + 1) + (xcd - r) * q) + off; }
;         const int nig = WGM * nN, gid = wgid / nig, fm = gid * WGM, gsz = (nM - fm) < WGM ? (nM - fm) : WGM;
;         u.pm = __builtin_amdgcn_readfirstlane(fm + ((wgid % nig) % gsz)); u.pn = __builtin_amdgcn_readfirstlane((wgid % nig) / gsz); return true;
.Lsgp1e_done:
	s_cmpk_lt_i32 s94, 0x200
	v_readfirstlane_b32 s6, v212
	s_movk_i32 s7, 0x800
	s_cselect_b64 s[0:1], -1, 0
	s_cmpk_gt_i32 s94, 0x1ff
	s_cbranch_scc1 .LBB0_529
	s_ashr_i32 s2, s94, 31
	s_lshr_b32 s2, s2, 29
	s_add_i32 s8, s94, s2
	s_and_b32 s2, s8, -8
	s_sub_i32 s9, s94, s2
	s_cmp_gt_i32 s9, -1
	s_mov_b64 s[2:3], -1
	s_cbranch_scc0 .LBB0_526
	s_lshl_b32 s10, s9, 6
	s_mov_b64 s[2:3], 0

; #define LAS __attribute__((address_space(3)))
; #define PG8_WAIT_V(n) asm volatile("s_waitcnt vmcnt(" #n ")" ::: "memory")
; #define PG8_BAR __builtin_amdgcn_s_barrier()
; template <class Epi>
; __device__ __forceinline__ void gemm_phase(LAS unsigned char* lds, const Gemm g, const StaticOrder& S, const Epi& E, const int tid) {
;     ...
;     PG8_WAIT_V(0);
;     PG8_BAR;
; __device__ __forceinline__ void xpose_item(const float* src, int ld, bf16_t* dst, int K, int k0, LAS float* scr, int lane, const float* gk) {
;     if (src) {
; #pragma unroll 8
;         for (int i = 0; i < 32; ++i) { const int kk = 2 * i + (lane >> 5); scr[kk * 33 + (lane & 31)] = __builtin_nontemporal_load(src + (size_t)(k0 + kk) * ld + (lane & 31)); }
;     } else {
; #pragma unroll 8
;         for (int i = 0; i < 32; ++i) { const int kk = 2 * i + (lane >> 5); scr[kk * 33 + (lane & 31)] = 0.f; }
;     }
;     const int c = lane & 7;
;     f32x4 g0 = (f32x4){1.f, 1.f, 1.f, 1.f}, g1 = g0;
;     if (gk) { g0 = *(const f32x4*)(gk + k0 + 8 * c); g1 = *(const f32x4*)(gk + k0 + 8 * c + 4); }
.LBB0_582:
	s_waitcnt vmcnt(0)
	s_barrier
	s_cmp_lg_u32 s76, 1
	s_cbranch_scc1 .Lsgp1x_done
	v_readlane_b32 s59, v255, 5
	s_cmpk_lg_i32 s59, 0x100
	s_cbranch_scc1 .Lsgp1x_done
	s_cmpk_lt_i32 s94, 0x80
	s_cbranch_scc1 .Lsgp1x_done
	s_lshl_b32 s59, s94, 3
	s_add_i32 s59, s59, s95
	s_mul_i32 s64, s95, 0x2100
	v_and_b32_e32 v2, 31, v200
	v_lshrrev_b32_e32 v3, 5, v200
	v_lshlrev_b32_e32 v4, 2, v2
	v_mul_u32_u24_e32 v6, 0x84, v3
	v_add3_u32 v6, v6, v4, s64
	v_and_b32_e32 v7, 7, v200
	v_lshrrev_b32_e32 v8, 3, v200
	v_mul_u32_u24_e32 v9, 0x420, v7
	v_lshl_add_u32 v9, v8, 2, v9
	v_add_u32_e32 v9, s64, v9
	s_cmpk_ge_i32 s59, 0x2c00
	s_cbranch_scc1 .Lxpg0p1x_end
	s_load_dwordx2 s[60:61], s[92:93], 0xb8
	s_load_dwordx2 s[62:63], s[92:93], 0xe8
	s_load_dwordx2 s[64:65], s[92:93], 0x18
	v_mov_b32_e32 v5, 0x5800
	v_mul_u32_u24_e32 v5, v3, v5
	v_add_u32_e32 v5, v5, v4
	v_mov_b32_e32 v10, 0x1000
	v_mul_u32_u24_e32 v10, v8, v10
	v_lshl_add_u32 v12, v7, 4, v10
	v_add_u32_e32 v13, 0x8000, v12
	v_add_u32_e32 v14, 0x10000, v12
	v_add_u32_e32 v15, 0x18000, v12
	s_waitcnt lgkmcnt(0)
	s_add_u32 s62, s62, 0x1cc00000
	s_addc_u32 s63, s63, 0
	s_add_u32 s64, s64, 0x0
	s_addc_u32 s65, s65, 0
	v_lshlrev_b32_e32 v16, 5, v7
	v_mov_b32_e32 v17, v0
	v_lshl_add_u64 v[16:17], s[64:65], 0, v[16:17]
	s_mul_hi_u32 s64, s59, 0xba2e8c
	s_mul_i32 s65, s64, 0x160
	s_sub_i32 s65, s59, s65
	s_mul_i32 s68, s64, 0x160000
	s_lshr_b32 s66, s65, 3
	s_lshl_b32 s66, s66, 9
	s_add_i32 s68, s68, s66
	s_and_b32 s66, s65, 3
	s_lshl_b32 s66, s66, 7
	s_add_i32 s68, s68, s66
	s_add_i32 s68, s68, 0x0
	s_bitcmp1_b32 s65, 2
	s_movk_i32 s33, 0xb8
	s_cselect_b32 s33, 0xc0, s33
	s_load_dwordx2 s[66:67], s[92:93], s33
	s_waitcnt lgkmcnt(0)
	s_add_u32 s66, s66, s68
	s_addc_u32 s67, s67, 0
	s_lshl_b32 s64, s64, 8
	s_mov_b32 s65, 0
	v_lshl_add_u64 v[18:19], s[64:65], 0, v[16:17]
	global_load_dwordx4 v[52:55], v[18:19], off
	global_load_dwordx4 v[56:59], v[18:19], off offset:16
	v_mov_b32_e32 v11, v5
	global_load_dword v20, v11, s[66:67] nt
	v_add_u32_e32 v11, 0xb000, v11
	global_load_dword v21, v11, s[66:67] nt
	v_add_u32_e32 v11, 0xb000, v11
	global_load_dword v22, v11, s[66:67] nt
	v_add_u32_e32 v11, 0xb000, v11
	global_load_dword v23, v11, s[66:67] nt
	v_add_u32_e32 v11, 0xb000, v11
	global_load_dword v24, v11, s[66:67] nt
	v_add_u32_e32 v11, 0xb000, v11
	global_load_dword v25, v11, s[66:67] nt
	v_add_u32_e32 v11, 0xb000, v11
	global_load_dword v26, v11, s[66:67] nt
	v_add_u32_e32 v11, 0xb000, v11
	global_load_dword v27, v11, s[66:67] nt
	v_add_u32_e32 v11, 0xb000, v11
	global_load_dword v28, v11, s[66:67] nt
	v_add_u32_e32 v11, 0xb000, v11
	global_load_dword v29, v11, s[66:67] nt
	v_add_u32_e32 v11, 0xb000, v11
	global_load_dword v30, v11, s[66:67] nt
	v_add_u32_e32 v11, 0xb000, v11
	global_load_dword v31, v11, s[66:67] nt
	v_add_u32_e32 v11, 0xb000, v11
	global_load_dword v32, v11, s[66:67] nt
	v_add_u32_e32 v11, 0xb000, v11
	global_load_dword v33, v11, s[66:67] nt
	v_add_u32_e32 v11, 0xb000, v11
	global_load_dword v34, v11, s[66:67] nt
	v_add_u32_e32 v11, 0xb000, v11
	global_load_dword v35, v11, s[66:67] nt
	v_add_u32_e32 v11, 0xb000, v11
	global_load_dword v36, v11, s[66:67] nt
	v_add_u32_e32 v11, 0xb000, v11
	global_load_dword v37, v11, s[66:67] nt
	v_add_u32_e32 v11, 0xb000, v11
	global_load_dword v38, v11, s[66:67] nt
	v_add_u32_e32 v11, 0xb000, v11
	global_load_dword v39, v11, s[66:67] nt
	v_add_u32_e32 v11, 0xb000, v11
	global_load_dword v40, v11, s[66:67] nt
	v_add_u32_e32 v11, 0xb000, v11
	global_load_dword v41, v11, s[66:67] nt
	v_add_u32_e32 v11, 0xb000, v11
	global_load_dword v42, v11, s[66:67] nt
	v_add_u32_e32 v11, 0xb000, v11
	global_load_dword v43, v11, s[66:67] nt
	v_add_u32_e32 v11, 0xb000, v11
	global_load_dword v44, v11, s[66:67] nt
	v_add_u32_e32 v11, 0xb000, v11
	global_load_dword v45, v11, s[66:67] nt
	v_add_u32_e32 v11, 0xb000, v11
	global_load_dword v46, v11, s[66:67] nt
	v_add_u32_e32 v11, 0xb000, v11
	global_load_dword v47, v11, s[66:67] nt
	v_add_u32_e32 v11, 0xb000, v11
	global_load_dword v48, v11, s[66:67] nt
	v_add_u32_e32 v11, 0xb000, v11
	global_load_dword v49, v11, s[66:67] nt
	v_add_u32_e32 v11, 0xb000, v11
	global_load_dword v50, v11, s[66:67] nt
	v_add_u32_e32 v11, 0xb000, v11
	global_load_dword v51, v11, s[66:67] nt

; __global__ void __launch_bounds__(512) mega(Args a_byval) {
;     ...
;         case 1: if (!PH_ON(1)) break; {
;             pg8::Gemm g{U, (const bf16_t*)(ws + WS_W_IN), T, 4096, 2048, 2048, 2048, 0}; pg8::StaticOrder S; S.init(T, 4096, G, bid);
;             EpiXY E{(bf16_t*)(ws + WS_XRPRE), (bf16_t*)(ws + WS_YG)}; pg8::gemm_phase(lds, g, S, E, tid);
;         } break;
.Lxpg0p1x_end:
	s_sub_i32 s59, s59, 0x2c00
	s_movk_i32 s33, 0x84
.Lsgp1x_done:
	s_load_dwordx2 s[38:39], s[92:93], 0xe8
.LBB0_583:
	s_mov_b64 s[0:1], 0

; #define LAS __attribute__((address_space(3)))
; __device__ __forceinline__ int xpose_all(const float* src, const float* src2, int ld, int K, int ndst, int nsrc, int mode, bf16_t* dst, int it, int NGW, LAS float* scr, int lane, const float* gvec = nullptr) {
;     const int nblk = ndst / 32, nitems = (K / 64) * nblk;
;     for (; it < nitems; it += NGW) {
; __global__ void __launch_bounds__(512) mega(Args a_byval) {
;     ...
;             it = xpose_all(a.in[23] + (size_t)lyr * D * DFF, a.in[24] + (size_t)lyr * D * DFF, DFF, 2048, 2 * DFF, 2 * DFF, 1, (bf16_t*)(ws + (lyr ? WS_W_GU : WS_W_GU0)), it, NGW, scr, lane, norm_ffn_g + lyr * D);
;             it = xpose_all(a.in[25] + (size_t)lyr * D * DFF, nullptr, 2048, DFF, 2048, 2048, 0, (bf16_t*)(ws + (lyr ? WS_W_D : WS_W_D0)), it, NGW, scr, lane);
.LBB0_633:
	s_mov_b64 s[8:9], 0x8300000
	s_mov_b64 s[14:15], 0x7b00000
	s_waitcnt lgkmcnt(0)
	s_mov_b64 s[16:17], 0x1f800000
	s_mov_b64 s[18:19], 0x1cc00000
	s_mov_b64 s[12:13], 0
	s_mov_b64 s[10:11], 0
	v_mov_b32_e32 v1, 0x1600
	s_cmpk_gt_u32 s28, 0x2bff
	v_mul_u32_u24_e32 v11, s12, v1
	s_cbranch_scc1 .LBB0_658
	v_readlane_b32 vcc_lo, v255, 5
	s_cmpk_lg_i32 vcc_lo, 0x100
	s_cbranch_scc1 .LBB0_645
	s_addk_i32 s28, 0x2c00
	s_branch .LBB0_658
